# wave 0 runs the T21 slot at raised priority (it now shares its SIMD with wave 4's emission)
# baseline (speedup 1.0000x reference)
.LBB0_238:
	s_setprio 2
	v_lshlrev_b32_e32 v90, 2, v94
	v_readlane_b32 s6, v253, 51
	v_mul_u32_u24_e32 v24, 0x90, v94
	v_and_b32_e32 v2, 32, v1
	v_add_u32_e32 v18, s6, v90
	v_lshl_add_u32 v19, v95, 11, v18
	ds_read2_b32 v[14:15], v19 offset0:32 offset1:96
	ds_read2_b32 v[10:11], v19 offset0:160 offset1:224
	v_readlane_b32 s6, v253, 53
	v_add_u32_e32 v20, 0x80, v19
	v_lshl_add_u32 v18, v89, 8, v18
	v_add3_u32 v26, s6, v24, v2
	ds_read2st64_b32 v[16:17], v20 offset0:4 offset1:5
	ds_read2st64_b32 v[12:13], v20 offset0:6 offset1:7
	ds_read_b128 v[2:5], v26
	ds_read_b128 v[6:9], v26 offset:16
	s_waitcnt lgkmcnt(4)
	v_cvt_pk_bf16_f32 v11, v10, v11
	v_cvt_pk_bf16_f32 v10, v14, v15
	s_waitcnt lgkmcnt(2)
	v_cvt_pk_bf16_f32 v13, v12, v13
	v_cvt_pk_bf16_f32 v12, v16, v17
	s_waitcnt lgkmcnt(0)
	v_cvt_pk_bf16_f32 v9, v8, v9
	v_cvt_pk_bf16_f32 v8, v6, v7
	v_cvt_pk_bf16_f32 v7, v4, v5
	v_cvt_pk_bf16_f32 v6, v2, v3
	ds_read_b32 v91, v18 offset:128
	ds_read2st64_b32 v[22:23], v20 offset0:17 offset1:18
	ds_read2st64_b32 v[30:31], v20 offset0:19 offset1:20
	ds_read2st64_b32 v[32:33], v20 offset0:21 offset1:22
	ds_read_b32 v93, v19 offset:6016
	ds_read_b128 v[18:21], v26 offset:64
	ds_read_b128 v[26:29], v26 offset:80
	v_mfma_f32_32x32x16_bf16 v[2:17], v[10:13], v[6:9], 0
	s_waitcnt lgkmcnt(3)
	v_cvt_pk_bf16_f32 v32, v31, v32
	s_waitcnt lgkmcnt(2)
	v_cvt_pk_bf16_f32 v33, v33, v93
	v_cvt_pk_bf16_f32 v31, v23, v30
	v_cvt_pk_bf16_f32 v30, v91, v22
	s_waitcnt lgkmcnt(1)
	v_cvt_pk_bf16_f32 v21, v20, v21
	v_cvt_pk_bf16_f32 v20, v18, v19
	v_lshlrev_b32_e32 v18, 2, v25
	v_readlane_b32 s6, v253, 52
	s_waitcnt lgkmcnt(0)
	v_cvt_pk_bf16_f32 v23, v28, v29
	v_cvt_pk_bf16_f32 v22, v26, v27
	v_add3_u32 v91, s6, v24, v18
	s_nop 0
	v_mfma_f32_32x32x16_bf16 v[2:17], v[30:33], v[20:23], v[2:17]
	ds_read_b128 v[18:21], v91
	ds_read_b128 v[22:25], v91 offset:32
	s_waitcnt lgkmcnt(0)
	v_cvt_pk_bf16_f32 v25, v24, v25
	v_cvt_pk_bf16_f32 v24, v22, v23
	v_cvt_pk_bf16_f32 v23, v20, v21
	v_cvt_pk_bf16_f32 v22, v18, v19
	s_nop 4
	v_cvt_pk_bf16_f32 v9, v8, v9
	v_cvt_pk_bf16_f32 v8, v6, v7
	v_cvt_pk_bf16_f32 v7, v4, v5
	v_cvt_pk_bf16_f32 v6, v2, v3
	s_nop 1
	v_mfma_f32_32x32x16_bf16 v[18:33], v[22:25], v[6:9], 0
	ds_read_b128 v[2:5], v91 offset:64
	ds_read_b128 v[6:9], v91 offset:96
	s_waitcnt lgkmcnt(0)
	v_cvt_pk_bf16_f32 v9, v8, v9
	v_cvt_pk_bf16_f32 v8, v6, v7
	v_cvt_pk_bf16_f32 v7, v4, v5
	v_cvt_pk_bf16_f32 v6, v2, v3
	v_cvt_pk_bf16_f32 v5, v16, v17
	v_cvt_pk_bf16_f32 v4, v14, v15
	v_cvt_pk_bf16_f32 v3, v12, v13
	v_cvt_pk_bf16_f32 v2, v10, v11
	s_nop 1
	v_mfma_f32_32x32x16_bf16 v[18:33], v[6:9], v[2:5], v[18:33]
	v_add_u32_e32 v2, 0, v90
	v_add_u32_e32 v3, 0x24a00, v2
	ds_read_b32 v3, v3
	v_add_u32_e32 v2, 0x24b00, v2
	ds_read_b32 v2, v2
	v_mul_u32_u24_e32 v5, 0x120, v95
	v_or_b32_e32 v5, v5, v94
	s_waitcnt lgkmcnt(1)
	s_nop 3
	v_mul_f32_e64 v4, v3, -v18
	v_lshl_add_u32 v5, v5, 1, 0
	s_waitcnt lgkmcnt(0)
	v_mul_f32_e32 v2, v3, v2
	v_cvt_pk_bf16_f32 v4, v4, s0
	v_add_u32_e32 v6, 0x19200, v5
	ds_write_b16 v6, v4
	v_mul_f32_e64 v4, v2, -v18
	v_cvt_pk_bf16_f32 v4, v4, s0
	v_add_u32_e32 v5, 0x1b600, v5
	ds_write_b16 v5, v4
	v_mul_f32_e64 v4, v3, -v19
	v_cvt_pk_bf16_f32 v4, v4, s0
	ds_write_b16 v6, v4 offset:144
	v_mul_f32_e64 v4, v2, -v19
	v_cvt_pk_bf16_f32 v4, v4, s0
	ds_write_b16 v5, v4 offset:144
	v_mul_f32_e64 v4, v3, -v20
	v_cvt_pk_bf16_f32 v4, v4, s0
	ds_write_b16 v6, v4 offset:288
	v_mul_f32_e64 v4, v2, -v20
	v_cvt_pk_bf16_f32 v4, v4, s0
	ds_write_b16 v5, v4 offset:288
	v_mul_f32_e64 v4, v3, -v21
	v_cvt_pk_bf16_f32 v4, v4, s0
	ds_write_b16 v6, v4 offset:432
	v_mul_f32_e64 v4, v2, -v21
	v_cvt_pk_bf16_f32 v4, v4, s0
	ds_write_b16 v5, v4 offset:432
	v_mul_f32_e64 v4, v3, -v22
	v_cvt_pk_bf16_f32 v4, v4, s0
	ds_write_b16 v6, v4 offset:1152
	v_mul_f32_e64 v4, v2, -v22
	v_cvt_pk_bf16_f32 v4, v4, s0
	ds_write_b16 v5, v4 offset:1152
	v_mul_f32_e64 v4, v3, -v23
	v_cvt_pk_bf16_f32 v4, v4, s0
	ds_write_b16 v6, v4 offset:1296
	v_mul_f32_e64 v4, v2, -v23
	v_cvt_pk_bf16_f32 v4, v4, s0
	ds_write_b16 v5, v4 offset:1296
	v_mul_f32_e64 v4, v3, -v24
	v_cvt_pk_bf16_f32 v4, v4, s0
	ds_write_b16 v6, v4 offset:1440
	v_mul_f32_e64 v4, v2, -v24
	v_cvt_pk_bf16_f32 v4, v4, s0
	ds_write_b16 v5, v4 offset:1440
	v_mul_f32_e64 v4, v3, -v25
	v_cvt_pk_bf16_f32 v4, v4, s0
	ds_write_b16 v6, v4 offset:1584
	v_mul_f32_e64 v4, v2, -v25
	v_cvt_pk_bf16_f32 v4, v4, s0
	ds_write_b16 v5, v4 offset:1584
	v_mul_f32_e64 v4, v3, -v26
	v_cvt_pk_bf16_f32 v4, v4, s0
	ds_write_b16 v6, v4 offset:2304
	v_mul_f32_e64 v4, v2, -v26
	v_cvt_pk_bf16_f32 v4, v4, s0
	ds_write_b16 v5, v4 offset:2304
	v_mul_f32_e64 v4, v3, -v27
	v_cvt_pk_bf16_f32 v4, v4, s0
	ds_write_b16 v6, v4 offset:2448
	v_mul_f32_e64 v4, v2, -v27
	v_cvt_pk_bf16_f32 v4, v4, s0
	ds_write_b16 v5, v4 offset:2448
	v_mul_f32_e64 v4, v3, -v28
	v_cvt_pk_bf16_f32 v4, v4, s0
	ds_write_b16 v6, v4 offset:2592
	v_mul_f32_e64 v4, v2, -v28
	v_cvt_pk_bf16_f32 v4, v4, s0
	ds_write_b16 v5, v4 offset:2592
	v_mul_f32_e64 v4, v3, -v29
	v_cvt_pk_bf16_f32 v4, v4, s0
	ds_write_b16 v6, v4 offset:2736
	v_mul_f32_e64 v4, v2, -v29
	v_cvt_pk_bf16_f32 v4, v4, s0
	ds_write_b16 v5, v4 offset:2736
	v_mul_f32_e64 v4, v3, -v30
	v_cvt_pk_bf16_f32 v4, v4, s0
	ds_write_b16 v6, v4 offset:3456
	v_mul_f32_e64 v4, v2, -v30
	v_cvt_pk_bf16_f32 v4, v4, s0
	ds_write_b16 v5, v4 offset:3456
	v_mul_f32_e64 v4, v3, -v31
	v_cvt_pk_bf16_f32 v4, v4, s0
	ds_write_b16 v6, v4 offset:3600
	v_mul_f32_e64 v4, v2, -v31
	v_cvt_pk_bf16_f32 v4, v4, s0
	ds_write_b16 v5, v4 offset:3600
	v_mul_f32_e64 v4, v3, -v32
	v_cvt_pk_bf16_f32 v4, v4, s0
	ds_write_b16 v6, v4 offset:3744
	v_mul_f32_e64 v4, v2, -v32
	v_mul_f32_e64 v3, v3, -v33
	v_mul_f32_e64 v2, v2, -v33
	v_cvt_pk_bf16_f32 v4, v4, s0
	v_cvt_pk_bf16_f32 v3, v3, s0
	v_cvt_pk_bf16_f32 v2, v2, s0
	v_mov_b32_e32 v18, v89
	ds_write_b16 v5, v4 offset:3744
	ds_write_b16 v6, v3 offset:3888
	ds_write_b16 v5, v2 offset:3888
	s_setprio 0
